# scan Y image stored by 32 lanes x 16 bytes (permlane32_swap pairs lanes l and l+32) instead of 64 lanes x 8 bytes
# speedup vs baseline: 1.0001x; 1.0001x over previous
; __device__ __forceinline__ void p3_rwkv_state(Frame& F, const Args& a) {
;     ...
;         for (int n = 0; n < NC; n += 2) { SP_STEP(C, N, n); SP_STEP(N, C, n + 1); }
.Lscan_loop:
	v_add_u32_e32 v80, s10, v77
	v_add_u32_e32 v81, s10, v78
	v_add_u32_e32 v82, s10, v79
	s_add_i32 s10, s10, 0x2800
	s_cmp_eq_u32 s10, 0x25800
	s_cselect_b32 s10, 0, s10
	v_mfma_f32_16x16x32_bf16 v[24:27], v[32:35], v[16:19], v[24:27]
	v_mfma_f32_16x16x32_bf16 v[28:31], v[40:43], v[16:19], v[28:31]
	v_mfma_f32_16x16x32_bf16 v[24:27], v[36:39], v[20:23], v[24:27]
	v_mfma_f32_16x16x32_bf16 v[28:31], v[44:47], v[20:23], v[28:31]
	ds_read_b128 v[32:35], v80
	ds_read_b128 v[36:39], v80 offset:1024
	ds_read_b128 v[40:43], v80 offset:2048
	ds_read_b128 v[44:47], v80 offset:3072
	ds_read2st64_b64 v[96:99], v81 offset0:16 offset1:17
	s_waitcnt lgkmcnt(10)
	v_pk_mul_f32 v[0:1], v[64:65], v[0:1]
	v_pk_mul_f32 v[2:3], v[66:67], v[2:3]
	v_pk_mul_f32 v[4:5], v[68:69], v[4:5]
	v_pk_mul_f32 v[6:7], v[70:71], v[6:7]
	v_pk_mul_f32 v[8:9], v[72:73], v[8:9]
	v_pk_mul_f32 v[10:11], v[74:75], v[10:11]
	v_pk_mul_f32 v[12:13], v[88:89], v[12:13]
	v_pk_mul_f32 v[14:15], v[90:91], v[14:15]
	ds_read_b128 v[64:67], v82 offset:9728
	ds_read_b128 v[68:71], v82 offset:9744
	ds_read_b128 v[72:75], v82 offset:9760
	ds_read_b128 v[88:91], v82 offset:9776
	v_cvt_pk_bf16_f32 v94, v24, v25
	v_cvt_pk_bf16_f32 v95, v26, v27
	s_waitcnt lgkmcnt(9)
	s_nop 1
	v_mfma_f32_16x16x32_bf16 v[0:3], v[48:51], v[92:95], v[0:3]
	v_mfma_f32_16x16x32_bf16 v[4:7], v[52:55], v[92:95], v[4:7]
	v_mfma_f32_16x16x32_bf16 v[8:11], v[56:59], v[92:95], v[8:11]
	v_mfma_f32_16x16x32_bf16 v[12:15], v[60:63], v[92:95], v[12:15]
	v_cvt_pk_bf16_f32 v84, v28, v29
	v_cvt_pk_bf16_f32 v85, v30, v31
	ds_read2st64_b64 v[48:51], v81 offset0:12 offset1:8
	ds_read2st64_b64 v[52:55], v81 offset0:13 offset1:9
	ds_read2st64_b64 v[56:59], v81 offset0:14 offset1:10
	ds_read2st64_b64 v[60:63], v81 offset0:15 offset1:11
	ds_read_b64 v[92:93], v81 offset:9216
	v_mov_b32_e32 v100, v84
	v_mov_b32_e32 v101, v85
	s_nop 1
	v_permlane32_swap_b32_e32 v84, v102
	v_permlane32_swap_b32_e32 v85, v103
	s_nop 1
	s_mov_b32 exec_hi, 0
	global_store_dwordx4 v77, v[100:103], s[8:9]
	s_mov_b64 exec, -1
	s_add_u32 s8, s8, 0x8000
	s_addc_u32 s9, s9, 0
	s_waitcnt lgkmcnt(9)
	v_lshlrev_b32_e32 v24, 16, v96
	v_and_b32_e32 v25, 0xffff0000, v96
	v_lshlrev_b32_e32 v26, 16, v97
	v_and_b32_e32 v27, 0xffff0000, v97
	v_lshlrev_b32_e32 v28, 16, v98
	v_and_b32_e32 v29, 0xffff0000, v98
	v_lshlrev_b32_e32 v30, 16, v99
	v_and_b32_e32 v31, 0xffff0000, v99
	v_cvt_pk_bf16_f32 v16, v0, v1
	v_cvt_pk_bf16_f32 v17, v2, v3
	v_cvt_pk_bf16_f32 v18, v4, v5
	v_cvt_pk_bf16_f32 v19, v6, v7
	v_cvt_pk_bf16_f32 v20, v8, v9
	v_cvt_pk_bf16_f32 v21, v10, v11
	v_cvt_pk_bf16_f32 v22, v12, v13
	v_cvt_pk_bf16_f32 v23, v14, v15
	v_add_u32_e32 v80, s10, v77
	v_add_u32_e32 v81, s10, v78
	v_add_u32_e32 v82, s10, v79
	s_add_i32 s10, s10, 0x2800
	s_cmp_eq_u32 s10, 0x25800
	s_cselect_b32 s10, 0, s10
	v_mfma_f32_16x16x32_bf16 v[24:27], v[32:35], v[16:19], v[24:27]
	v_mfma_f32_16x16x32_bf16 v[28:31], v[40:43], v[16:19], v[28:31]
	v_mfma_f32_16x16x32_bf16 v[24:27], v[36:39], v[20:23], v[24:27]
	v_mfma_f32_16x16x32_bf16 v[28:31], v[44:47], v[20:23], v[28:31]
	ds_read_b128 v[32:35], v80
	ds_read_b128 v[36:39], v80 offset:1024
	ds_read_b128 v[40:43], v80 offset:2048
	ds_read_b128 v[44:47], v80 offset:3072
	ds_read2st64_b64 v[96:99], v81 offset0:16 offset1:17
	s_waitcnt lgkmcnt(10)
	v_pk_mul_f32 v[0:1], v[64:65], v[0:1]
	v_pk_mul_f32 v[2:3], v[66:67], v[2:3]
	v_pk_mul_f32 v[4:5], v[68:69], v[4:5]
	v_pk_mul_f32 v[6:7], v[70:71], v[6:7]
	v_pk_mul_f32 v[8:9], v[72:73], v[8:9]
	v_pk_mul_f32 v[10:11], v[74:75], v[10:11]
	v_pk_mul_f32 v[12:13], v[88:89], v[12:13]
	v_pk_mul_f32 v[14:15], v[90:91], v[14:15]
	ds_read_b128 v[64:67], v82 offset:9728
	ds_read_b128 v[68:71], v82 offset:9744
	ds_read_b128 v[72:75], v82 offset:9760
	ds_read_b128 v[88:91], v82 offset:9776
	v_cvt_pk_bf16_f32 v94, v24, v25
	v_cvt_pk_bf16_f32 v95, v26, v27
	s_waitcnt lgkmcnt(9)
	s_nop 1
	v_mfma_f32_16x16x32_bf16 v[0:3], v[48:51], v[92:95], v[0:3]
	v_mfma_f32_16x16x32_bf16 v[4:7], v[52:55], v[92:95], v[4:7]
	v_mfma_f32_16x16x32_bf16 v[8:11], v[56:59], v[92:95], v[8:11]
	v_mfma_f32_16x16x32_bf16 v[12:15], v[60:63], v[92:95], v[12:15]
	v_cvt_pk_bf16_f32 v84, v28, v29
	v_cvt_pk_bf16_f32 v85, v30, v31
	ds_read2st64_b64 v[48:51], v81 offset0:12 offset1:8
	ds_read2st64_b64 v[52:55], v81 offset0:13 offset1:9
	ds_read2st64_b64 v[56:59], v81 offset0:14 offset1:10
	ds_read2st64_b64 v[60:63], v81 offset0:15 offset1:11
	ds_read_b64 v[92:93], v81 offset:9216
	v_mov_b32_e32 v100, v84
	v_mov_b32_e32 v101, v85
	s_nop 1
	v_permlane32_swap_b32_e32 v84, v102
	v_permlane32_swap_b32_e32 v85, v103
	s_nop 1
	s_mov_b32 exec_hi, 0
	global_store_dwordx4 v77, v[100:103], s[8:9]
	s_mov_b64 exec, -1
	s_add_u32 s8, s8, 0x8000
	s_addc_u32 s9, s9, 0
	s_waitcnt lgkmcnt(9)
	v_lshlrev_b32_e32 v24, 16, v96
	v_and_b32_e32 v25, 0xffff0000, v96
	v_lshlrev_b32_e32 v26, 16, v97
	v_and_b32_e32 v27, 0xffff0000, v97
	v_lshlrev_b32_e32 v28, 16, v98
	v_and_b32_e32 v29, 0xffff0000, v98
	v_lshlrev_b32_e32 v30, 16, v99
	v_and_b32_e32 v31, 0xffff0000, v99
	v_cvt_pk_bf16_f32 v16, v0, v1
	v_cvt_pk_bf16_f32 v17, v2, v3
	v_cvt_pk_bf16_f32 v18, v4, v5
	v_cvt_pk_bf16_f32 v19, v6, v7
	v_cvt_pk_bf16_f32 v20, v8, v9
	v_cvt_pk_bf16_f32 v21, v10, v11
	v_cvt_pk_bf16_f32 v22, v12, v13
	v_cvt_pk_bf16_f32 v23, v14, v15
	s_barrier
	s_add_i32 s11, s11, 2
	s_cmpk_lt_u32 s11, 0x400
	s_cbranch_scc1 .Lscan_loop
	s_branch .LBB0_456

; __device__ __forceinline__ f32x4 bf4(v2u u) { return (f32x4){bflo(u.x), bfhi(u.x), bflo(u.y), bfhi(u.y)}; }
; __device__ __forceinline__ void p3_gn_chunk(const Args& a, int ch, int lane) {
;     const int n = lane & 15, rg = lane >> 4, head = ch & 15, c0 = head * 64 + 4 * n; const int t0 = (ch >> 4) * 16 + 4 * rg;
;     const bf16* YR = (const bf16*)(a.ws + WS_YR); const bf16* ZB = (const bf16*)(a.ws + WS_ZB); bf16* Y = (bf16*)(a.ws + WS_XN); const float* RK = (const float*)(a.ws + WS_RK);
;     const f32x4 lw = ld4(a.in[16] + c0), lb = ld4(a.in[17] + c0);
;     f32x4 vimg[4];
; #pragma unroll
;     for (int cb = 0; cb < 4; ++cb) vimg[cb] = bf4(*(const v2u*)(a.ws + WS_VS + (size_t)ch * 2048 + cb * 512 + lane * 8));
; #pragma unroll
;     for (int e = 0; e < 4; ++e) { const int t = t0 + e;
;         f32x4 y = bf4(*(const v2u*)(YR + (size_t)t * 1024 + c0));
.LBB0_638:
	s_or_b64 exec, exec, s[0:1]
	v_readlane_b32 s0, v254, 39
	v_readlane_b32 s1, v254, 40
	v_readlane_b32 s60, v254, 36
	v_readlane_b32 s12, v254, 6
	s_waitcnt lgkmcnt(0)
	s_barrier
	v_mbcnt_lo_u32_b32 v0, -1, 0
	v_mbcnt_hi_u32_b32 v0, -1, v0
	s_and_b64 vcc, exec, s[0:1]
	v_readlane_b32 s61, v254, 37
	v_readlane_b32 s13, v254, 7
	v_readlane_b32 s14, v254, 8
	v_readlane_b32 s15, v254, 9
	v_readlane_b32 s24, v254, 18
	v_readlane_b32 s25, v254, 19
	v_readlane_b32 s26, v254, 20
	v_readlane_b32 s27, v254, 21
	v_readlane_b32 s16, v254, 10
	v_readlane_b32 s17, v254, 11
	v_readlane_b32 s18, v254, 12
	v_readlane_b32 s19, v254, 13
	v_readlane_b32 s20, v254, 14
	v_readlane_b32 s21, v254, 15
	v_readlane_b32 s22, v254, 16
	v_readlane_b32 s23, v254, 17
	s_cbranch_vccnz .LBB0_641
	s_add_u32 s2, s90, 0x3d00000
	s_addc_u32 s3, s91, 0
	s_ashr_i32 s65, s64, 31
	v_lshlrev_b32_e32 v1, 2, v0
	s_lshl_b64 s[0:1], s[64:65], 11
	v_and_b32_e32 v30, 60, v1
	v_ashrrev_i32_e32 v1, 2, v0
	v_lshlrev_b32_e32 v0, 3, v0
	s_add_u32 s0, s90, s0
	v_and_b32_e32 v31, -4, v1
	v_ashrrev_i32_e32 v1, 31, v0
	s_addc_u32 s1, s91, s1
	v_bfe_u32 v132, v0, 3, 5
	v_lshlrev_b32_e32 v132, 4, v132
	v_bfe_u32 v133, v0, 8, 1
	v_lshl_or_b32 v132, v133, 3, v132
	v_mov_b32_e32 v133, 0
	v_lshl_add_u64 v[130:131], s[72:73], 0, v[132:133]
	s_mov_b32 s98, 0x05040100
	s_mov_b32 s99, 0x07060302
	s_mov_b32 s101, 0
	v_lshl_add_u64 v[0:1], s[0:1], 0, v[0:1]
	s_mov_b64 s[0:1], 0x1d000000
	s_ashr_i32 s43, s42, 31
	v_lshl_add_u64 v[8:9], v[0:1], 0, s[0:1]
	s_lshl_b64 s[0:1], s[42:43], 11
	v_mov_b32_e32 v11, 0
	s_movk_i32 s6, 0x2800
	v_mov_b64_e32 v[12:13], s[90:91]
	s_mov_b32 s7, 0xf002000
	v_mov_b32_e32 v32, 0x3a27c5ac
	s_mov_b32 s8, s64
